# F2 last partial round as 4-way split-K on all 256 workgroups (f32 partials via d_ws, per-wave flags), F2 start delay removed; on top of peel+noprio
# speedup vs baseline: 1.0117x; 1.0043x over previous
.LBB0_1252:
	s_abs_i32 s3, s10
	v_cvt_f32_u32_e32 v0, s3
	s_sub_i32 s11, 0, s3
	v_rcp_iflag_f32_e32 v0, v0
	s_nop 0
	v_mul_f32_e32 v0, 0x4f7ffffe, v0
	v_cvt_u32_f32_e32 v0, v0
	s_nop 0
	v_readfirstlane_b32 s14, v0
	s_mul_i32 s11, s11, s14
	s_mul_hi_u32 s11, s14, s11
	s_add_i32 s14, s14, s11
	s_mul_hi_u32 s11, s14, 0x440
	s_mul_i32 s11, s11, s3
	s_sub_i32 s11, 0x440, s11
	s_sub_i32 s14, s11, s3
	s_cmp_ge_u32 s11, s3
	s_cselect_b32 s11, s14, s11
	s_sub_i32 s14, s11, s3
	s_cmp_ge_u32 s11, s3
	s_cselect_b32 s3, s14, s11
	s_cmp_eq_u32 s3, 0
	s_cbranch_scc1 .LBB0_1250
	s_ashr_i32 s11, s10, 3
	s_abs_i32 s10, s11
	v_cvt_f32_u32_e32 v0, s10
	s_sub_i32 s16, 0, s10
	s_abs_i32 s14, s3
	s_xor_b32 s15, s3, s11
	v_rcp_iflag_f32_e32 v0, v0
	s_ashr_i32 s15, s15, 31
	v_mul_f32_e32 v0, 0x4f7ffffe, v0
	v_cvt_u32_f32_e32 v0, v0
	s_nop 0
	v_readfirstlane_b32 s17, v0
	s_mul_i32 s16, s16, s17
	s_mul_hi_u32 s16, s17, s16
	s_add_i32 s17, s17, s16
	s_mul_hi_u32 s16, s14, s17
	s_mul_i32 s17, s16, s10
	s_sub_i32 s14, s14, s17
	s_add_i32 s18, s16, 1
	s_sub_i32 s17, s14, s10
	s_cmp_ge_u32 s14, s10
	s_cselect_b32 s16, s18, s16
	s_cselect_b32 s14, s17, s14
	s_add_i32 s17, s16, 1
	s_cmp_ge_u32 s14, s10
	s_cselect_b32 s10, s17, s16
	s_xor_b32 s10, s10, s15
	s_sub_i32 s10, s10, s15
	s_mul_i32 s11, s10, s11
	s_sub_i32 s3, s3, s11
	s_cmp_lg_u32 s3, 0
	s_cbranch_scc1 .LBB0_1250
	s_and_b32 s2, s2, 7
	s_branch .LBB0_1250

.LBB0_1276:
	s_and_b64 vcc, exec, s[74:75]
	s_cbranch_vccz .LBB0_1279
	s_cmp_lt_i32 s54, 5
	s_cbranch_scc0 .LBB0_1279
	s_add_i32 s4, s54, s91
	s_mul_i32 s4, s4, s3
	s_add_i32 s77, s4, s89
	s_cmp_eq_u32 s54, 4
	s_cbranch_scc0 .Lsk_nt1
	s_and_b32 s4, s1, 7
	s_lshl_b32 s4, s4, 5
	s_lshr_b32 s5, s1, 3
	s_add_i32 s4, s4, s5
	s_lshr_b32 s4, s4, 2
	s_add_i32 s77, s4, 0x80
	s_cmp_ge_u32 s4, 32
	s_cselect_b32 s4, 0x80, 0
	s_add_i32 s77, s77, s4
.Lsk_nt1:
	s_mov_b64 s[4:5], -1

.LBB0_1285:
	s_cmp_eq_u32 s54, 4
	s_cbranch_scc0 .Lsk_nt2
	s_bfe_u32 s67, s1, 0x20003
	s_mulk_i32 s67, 0xb00
	s_add_u32 s74, s74, s67
	s_addc_u32 s75, s75, 0
	s_add_u32 s76, s76, s67
	s_addc_u32 s77, s77, 0

.LBB0_1289:
	s_lshl_b32 s80, s96, 8
	s_ashr_i32 s81, s80, 31
	s_lshl_b64 s[86:87], s[80:81], 2
	s_add_u32 s84, s84, s86
	s_addc_u32 s85, s85, s87
	s_add_i32 m0, s94, s41
	s_add_u32 s81, s82, 0x100
	global_load_lds_dwordx4 v239, s[84:85]
	s_addc_u32 s96, s83, 0
	s_cmp_eq_u32 s54, 5
	s_cselect_b32 vcc_lo, 64, -2
	s_add_u32 s82, s78, 0x100
	s_addc_u32 s83, s79, 0
	s_add_i32 s94, 0, 0x10000
	s_cmpk_eq_i32 vcc_lo, 0x54
	s_cselect_b32 s87, s75, s83
	s_cselect_b32 s86, s74, s82
	s_cselect_b32 s85, s77, s96
	s_cselect_b32 s84, s76, s81
	s_add_i32 vcc_hi, 0, 0x14000
	v_add_u32_e32 v96, s94, v238
	v_add_u32_e32 v140, vcc_hi, v238
	ds_read_b128 v[64:67], v96
	ds_read_b128 v[72:75], v96 offset:1024
	ds_read_b128 v[88:91], v96 offset:2048
	ds_read_b128 v[96:99], v96 offset:3072
	ds_read_b128 v[108:111], v140
	ds_read_b128 v[116:119], v140 offset:1024
	ds_read_b128 v[128:131], v140 offset:2048
	ds_read_b128 v[140:143], v140 offset:3072
	v_lshl_add_u64 v[192:193], s[78:79], 0, v[230:231]
	s_add_i32 m0, s29, 0xc000
	ds_read_b128 v[152:155], v240
	ds_read_b128 v[156:159], v240 offset:1024
	ds_read_b128 v[160:163], v240 offset:2048
	ds_read_b128 v[164:167], v240 offset:3072
	ds_read_b128 v[168:171], v240 offset:4096
	ds_read_b128 v[180:183], v240 offset:5120
	ds_read_b128 v[184:187], v240 offset:6144
	ds_read_b128 v[188:191], v240 offset:7168
	global_load_lds_dwordx4 v[192:193], off
	v_lshl_add_u64 v[192:193], s[78:79], 0, v[232:233]
	s_add_i32 m0, s29, 0xe000
	s_nop 0
	global_load_lds_dwordx4 v[192:193], off
	s_waitcnt vmcnt(8)
	s_waitcnt lgkmcnt(0)
	s_barrier
	s_waitcnt lgkmcnt(0)
	v_mfma_f32_16x16x32_bf16 v[176:179], v[64:67], v[152:155], 0
	v_mfma_f32_16x16x32_bf16 v[172:175], v[88:91], v[152:155], 0
	v_mfma_f32_16x16x32_bf16 v[136:139], v[64:67], v[160:163], 0
	v_mfma_f32_16x16x32_bf16 v[132:135], v[88:91], v[160:163], 0
	v_mfma_f32_16x16x32_bf16 v[112:115], v[64:67], v[168:171], 0
	v_mfma_f32_16x16x32_bf16 v[104:107], v[88:91], v[168:171], 0
	v_mfma_f32_16x16x32_bf16 v[84:87], v[64:67], v[184:187], 0
	v_mfma_f32_16x16x32_bf16 v[80:83], v[88:91], v[184:187], 0
	v_mfma_f32_16x16x32_bf16 v[176:179], v[72:75], v[156:159], v[176:179]
	v_mfma_f32_16x16x32_bf16 v[172:175], v[96:99], v[156:159], v[172:175]
	v_mfma_f32_16x16x32_bf16 v[136:139], v[72:75], v[164:167], v[136:139]
	v_mfma_f32_16x16x32_bf16 v[132:135], v[96:99], v[164:167], v[132:135]
	v_mfma_f32_16x16x32_bf16 v[112:115], v[72:75], v[180:183], v[112:115]
	v_mfma_f32_16x16x32_bf16 v[104:107], v[96:99], v[180:183], v[104:107]
	v_mfma_f32_16x16x32_bf16 v[84:87], v[72:75], v[188:191], v[84:87]
	v_mfma_f32_16x16x32_bf16 v[80:83], v[96:99], v[188:191], v[80:83]
	v_mfma_f32_16x16x32_bf16 v[148:151], v[108:111], v[152:155], 0
	v_mfma_f32_16x16x32_bf16 v[144:147], v[128:131], v[152:155], 0
	v_mfma_f32_16x16x32_bf16 v[124:127], v[108:111], v[160:163], 0
	v_mfma_f32_16x16x32_bf16 v[120:123], v[128:131], v[160:163], 0
	v_mfma_f32_16x16x32_bf16 v[100:103], v[108:111], v[168:171], 0
	v_mfma_f32_16x16x32_bf16 v[92:95], v[128:131], v[168:171], 0
	v_mfma_f32_16x16x32_bf16 v[76:79], v[108:111], v[184:187], 0
	v_mfma_f32_16x16x32_bf16 v[68:71], v[128:131], v[184:187], 0
	v_mfma_f32_16x16x32_bf16 v[148:151], v[116:119], v[156:159], v[148:151]
	v_mfma_f32_16x16x32_bf16 v[144:147], v[140:143], v[156:159], v[144:147]
	v_mfma_f32_16x16x32_bf16 v[124:127], v[116:119], v[164:167], v[124:127]
	v_mfma_f32_16x16x32_bf16 v[120:123], v[140:143], v[164:167], v[120:123]
	v_mfma_f32_16x16x32_bf16 v[100:103], v[116:119], v[180:183], v[100:103]
	v_mfma_f32_16x16x32_bf16 v[92:95], v[140:143], v[180:183], v[92:95]
	v_mfma_f32_16x16x32_bf16 v[76:79], v[116:119], v[188:191], v[76:79]
	v_mfma_f32_16x16x32_bf16 v[68:71], v[140:143], v[188:191], v[68:71]
	s_barrier
	s_add_i32 s78, s94, s2
	v_lshl_add_u64 v[192:193], s[84:85], 0, v[216:217]
	s_mov_b32 m0, s78
	ds_read_b128 v[152:155], v240 offset:16384
	ds_read_b128 v[156:159], v240 offset:17408
	ds_read_b128 v[160:163], v240 offset:18432
	ds_read_b128 v[164:167], v240 offset:19456
	ds_read_b128 v[168:171], v240 offset:20480
	ds_read_b128 v[180:183], v240 offset:21504
	ds_read_b128 v[184:187], v240 offset:22528
	ds_read_b128 v[188:191], v240 offset:23552
	global_load_lds_dwordx4 v[192:193], off
	s_add_i32 m0, s78, 0x2000
	s_add_u32 s78, s84, 0x160000
	v_lshl_add_u64 v[194:195], s[84:85], 0, v[228:229]
	s_addc_u32 s79, s85, 0
	s_add_i32 s94, vcc_hi, s2
	global_load_lds_dwordx4 v[194:195], off
	v_lshl_add_u64 v[196:197], s[78:79], 0, v[216:217]
	s_mov_b32 m0, s94
	v_lshl_add_u64 v[198:199], s[86:87], 0, v[226:227]
	global_load_lds_dwordx4 v[196:197], off
	v_lshl_add_u64 v[196:197], s[78:79], 0, v[228:229]
	s_add_i32 m0, s94, 0x2000
	s_nop 0
	global_load_lds_dwordx4 v[196:197], off
	v_lshl_add_u64 v[196:197], s[86:87], 0, v[224:225]
	s_mov_b32 m0, s29
	s_nop 0
	global_load_lds_dwordx4 v[196:197], off
	s_mov_b32 m0, s34
	s_nop 0
	global_load_lds_dwordx4 v[198:199], off
	s_waitcnt vmcnt(8)
	s_waitcnt lgkmcnt(0)
	s_barrier
	s_waitcnt lgkmcnt(0)
	v_mfma_f32_16x16x32_bf16 v[60:63], v[64:67], v[152:155], 0
	v_mfma_f32_16x16x32_bf16 v[56:59], v[88:91], v[152:155], 0
	v_mfma_f32_16x16x32_bf16 v[44:47], v[64:67], v[160:163], 0
	v_mfma_f32_16x16x32_bf16 v[40:43], v[88:91], v[160:163], 0
	v_mfma_f32_16x16x32_bf16 v[28:31], v[64:67], v[168:171], 0
	v_mfma_f32_16x16x32_bf16 v[24:27], v[88:91], v[168:171], 0
	v_mfma_f32_16x16x32_bf16 v[12:15], v[64:67], v[184:187], 0
	v_mfma_f32_16x16x32_bf16 v[8:11], v[88:91], v[184:187], 0
	v_mfma_f32_16x16x32_bf16 v[60:63], v[72:75], v[156:159], v[60:63]
	v_mfma_f32_16x16x32_bf16 v[56:59], v[96:99], v[156:159], v[56:59]
	v_mfma_f32_16x16x32_bf16 v[44:47], v[72:75], v[164:167], v[44:47]
	v_mfma_f32_16x16x32_bf16 v[40:43], v[96:99], v[164:167], v[40:43]
	v_mfma_f32_16x16x32_bf16 v[28:31], v[72:75], v[180:183], v[28:31]
	v_mfma_f32_16x16x32_bf16 v[24:27], v[96:99], v[180:183], v[24:27]
	v_mfma_f32_16x16x32_bf16 v[12:15], v[72:75], v[188:191], v[12:15]
	v_mfma_f32_16x16x32_bf16 v[8:11], v[96:99], v[188:191], v[8:11]
	v_mfma_f32_16x16x32_bf16 v[52:55], v[108:111], v[152:155], 0
	v_mfma_f32_16x16x32_bf16 v[48:51], v[128:131], v[152:155], 0
	v_mfma_f32_16x16x32_bf16 v[36:39], v[108:111], v[160:163], 0
	v_mfma_f32_16x16x32_bf16 v[32:35], v[128:131], v[160:163], 0
	v_mfma_f32_16x16x32_bf16 v[20:23], v[108:111], v[168:171], 0
	v_mfma_f32_16x16x32_bf16 v[16:19], v[128:131], v[168:171], 0
	v_mfma_f32_16x16x32_bf16 v[4:7], v[108:111], v[184:187], 0
	v_mfma_f32_16x16x32_bf16 v[0:3], v[128:131], v[184:187], 0
	v_mfma_f32_16x16x32_bf16 v[52:55], v[116:119], v[156:159], v[52:55]
	v_mfma_f32_16x16x32_bf16 v[48:51], v[140:143], v[156:159], v[48:51]
	v_mfma_f32_16x16x32_bf16 v[36:39], v[116:119], v[164:167], v[36:39]
	v_mfma_f32_16x16x32_bf16 v[32:35], v[140:143], v[164:167], v[32:35]
	v_mfma_f32_16x16x32_bf16 v[20:23], v[116:119], v[180:183], v[20:23]
	v_mfma_f32_16x16x32_bf16 v[16:19], v[140:143], v[180:183], v[16:19]
	v_mfma_f32_16x16x32_bf16 v[4:7], v[116:119], v[188:191], v[4:7]
	v_mfma_f32_16x16x32_bf16 v[0:3], v[140:143], v[188:191], v[0:3]
	s_barrier
	s_add_i32 s94, 0, 0x18000
	s_add_i32 vcc_hi, 0, 0x1c000
	v_add_u32_e32 v96, s94, v238
	v_add_u32_e32 v140, vcc_hi, v238
	ds_read_b128 v[64:67], v96
	ds_read_b128 v[72:75], v96 offset:1024
	ds_read_b128 v[88:91], v96 offset:2048
	ds_read_b128 v[96:99], v96 offset:3072
	ds_read_b128 v[108:111], v140
	ds_read_b128 v[116:119], v140 offset:1024
	ds_read_b128 v[128:131], v140 offset:2048
	ds_read_b128 v[140:143], v140 offset:3072
	s_add_u32 s78, s86, 0x160000
	s_addc_u32 s79, s87, 0
	s_mov_b32 m0, s35
	v_lshl_add_u64 v[200:201], s[78:79], 0, v[224:225]
	ds_read_b128 v[152:155], v240 offset:32768
	ds_read_b128 v[156:159], v240 offset:33792
	ds_read_b128 v[160:163], v240 offset:34816
	ds_read_b128 v[164:167], v240 offset:35840
	ds_read_b128 v[168:171], v240 offset:36864
	ds_read_b128 v[180:183], v240 offset:37888
	ds_read_b128 v[184:187], v240 offset:38912
	ds_read_b128 v[188:191], v240 offset:39936
	global_load_lds_dwordx4 v[200:201], off
	v_lshl_add_u64 v[200:201], s[78:79], 0, v[226:227]
	s_mov_b32 m0, s38
	s_nop 0
	global_load_lds_dwordx4 v[200:201], off
	s_waitcnt vmcnt(8)
	s_waitcnt lgkmcnt(0)
	s_barrier
	s_waitcnt lgkmcnt(0)
	v_mfma_f32_16x16x32_bf16 v[176:179], v[64:67], v[152:155], v[176:179]
	v_mfma_f32_16x16x32_bf16 v[172:175], v[88:91], v[152:155], v[172:175]
	v_mfma_f32_16x16x32_bf16 v[136:139], v[64:67], v[160:163], v[136:139]
	v_mfma_f32_16x16x32_bf16 v[132:135], v[88:91], v[160:163], v[132:135]
	v_mfma_f32_16x16x32_bf16 v[112:115], v[64:67], v[168:171], v[112:115]
	v_mfma_f32_16x16x32_bf16 v[104:107], v[88:91], v[168:171], v[104:107]
	v_mfma_f32_16x16x32_bf16 v[84:87], v[64:67], v[184:187], v[84:87]
	v_mfma_f32_16x16x32_bf16 v[80:83], v[88:91], v[184:187], v[80:83]
	v_mfma_f32_16x16x32_bf16 v[176:179], v[72:75], v[156:159], v[176:179]
	v_mfma_f32_16x16x32_bf16 v[172:175], v[96:99], v[156:159], v[172:175]
	v_mfma_f32_16x16x32_bf16 v[136:139], v[72:75], v[164:167], v[136:139]
	v_mfma_f32_16x16x32_bf16 v[132:135], v[96:99], v[164:167], v[132:135]
	v_mfma_f32_16x16x32_bf16 v[112:115], v[72:75], v[180:183], v[112:115]
	v_mfma_f32_16x16x32_bf16 v[104:107], v[96:99], v[180:183], v[104:107]
	v_mfma_f32_16x16x32_bf16 v[84:87], v[72:75], v[188:191], v[84:87]
	v_mfma_f32_16x16x32_bf16 v[80:83], v[96:99], v[188:191], v[80:83]
	v_mfma_f32_16x16x32_bf16 v[148:151], v[108:111], v[152:155], v[148:151]
	v_mfma_f32_16x16x32_bf16 v[144:147], v[128:131], v[152:155], v[144:147]
	v_mfma_f32_16x16x32_bf16 v[124:127], v[108:111], v[160:163], v[124:127]
	v_mfma_f32_16x16x32_bf16 v[120:123], v[128:131], v[160:163], v[120:123]
	v_mfma_f32_16x16x32_bf16 v[100:103], v[108:111], v[168:171], v[100:103]
	v_mfma_f32_16x16x32_bf16 v[92:95], v[128:131], v[168:171], v[92:95]
	v_mfma_f32_16x16x32_bf16 v[76:79], v[108:111], v[184:187], v[76:79]
	v_mfma_f32_16x16x32_bf16 v[68:71], v[128:131], v[184:187], v[68:71]
	v_mfma_f32_16x16x32_bf16 v[148:151], v[116:119], v[156:159], v[148:151]
	v_mfma_f32_16x16x32_bf16 v[144:147], v[140:143], v[156:159], v[144:147]
	v_mfma_f32_16x16x32_bf16 v[124:127], v[116:119], v[164:167], v[124:127]
	v_mfma_f32_16x16x32_bf16 v[120:123], v[140:143], v[164:167], v[120:123]
	v_mfma_f32_16x16x32_bf16 v[100:103], v[116:119], v[180:183], v[100:103]
	v_mfma_f32_16x16x32_bf16 v[92:95], v[140:143], v[180:183], v[92:95]
	v_mfma_f32_16x16x32_bf16 v[76:79], v[116:119], v[188:191], v[76:79]
	v_mfma_f32_16x16x32_bf16 v[68:71], v[140:143], v[188:191], v[68:71]
	s_barrier
	s_add_i32 s78, s94, s2
	v_lshl_add_u64 v[192:193], v[192:193], 0, s[30:31]
	s_mov_b32 m0, s78
	ds_read_b128 v[152:155], v240 offset:49152
	ds_read_b128 v[156:159], v240 offset:50176
	ds_read_b128 v[160:163], v240 offset:51200
	ds_read_b128 v[164:167], v240 offset:52224
	ds_read_b128 v[168:171], v240 offset:53248
	ds_read_b128 v[180:183], v240 offset:54272
	ds_read_b128 v[184:187], v240 offset:55296
	ds_read_b128 v[188:191], v240 offset:56320
	global_load_lds_dwordx4 v[192:193], off
	s_add_i32 m0, s78, 0x2000
	s_add_u32 s78, s84, 0x160080
	v_lshl_add_u64 v[192:193], v[194:195], 0, s[30:31]
	s_addc_u32 s79, s85, 0
	s_add_i32 s84, vcc_hi, s2
	global_load_lds_dwordx4 v[192:193], off
	v_lshl_add_u64 v[192:193], s[78:79], 0, v[216:217]
	s_mov_b32 m0, s84
	s_nop 0
	global_load_lds_dwordx4 v[192:193], off
	v_lshl_add_u64 v[192:193], s[78:79], 0, v[228:229]
	s_add_i32 m0, s84, 0x2000
	s_nop 0
	global_load_lds_dwordx4 v[192:193], off
	v_lshl_add_u64 v[192:193], v[196:197], 0, s[30:31]
	s_mov_b32 m0, s60
	s_nop 0
	global_load_lds_dwordx4 v[192:193], off
	v_lshl_add_u64 v[192:193], v[198:199], 0, s[30:31]
	s_mov_b32 m0, s61
	s_nop 0
	global_load_lds_dwordx4 v[192:193], off
	s_waitcnt vmcnt(8)
	s_waitcnt lgkmcnt(0)
	s_barrier
	s_waitcnt lgkmcnt(0)
	v_mfma_f32_16x16x32_bf16 v[60:63], v[64:67], v[152:155], v[60:63]
	v_mfma_f32_16x16x32_bf16 v[56:59], v[88:91], v[152:155], v[56:59]
	v_mfma_f32_16x16x32_bf16 v[44:47], v[64:67], v[160:163], v[44:47]
	v_mfma_f32_16x16x32_bf16 v[40:43], v[88:91], v[160:163], v[40:43]
	v_mfma_f32_16x16x32_bf16 v[28:31], v[64:67], v[168:171], v[28:31]
	v_mfma_f32_16x16x32_bf16 v[24:27], v[88:91], v[168:171], v[24:27]
	v_mfma_f32_16x16x32_bf16 v[12:15], v[64:67], v[184:187], v[12:15]
	v_mfma_f32_16x16x32_bf16 v[8:11], v[88:91], v[184:187], v[8:11]
	v_mfma_f32_16x16x32_bf16 v[60:63], v[72:75], v[156:159], v[60:63]
	v_mfma_f32_16x16x32_bf16 v[56:59], v[96:99], v[156:159], v[56:59]
	v_mfma_f32_16x16x32_bf16 v[44:47], v[72:75], v[164:167], v[44:47]
	v_mfma_f32_16x16x32_bf16 v[40:43], v[96:99], v[164:167], v[40:43]
	v_mfma_f32_16x16x32_bf16 v[28:31], v[72:75], v[180:183], v[28:31]
	v_mfma_f32_16x16x32_bf16 v[24:27], v[96:99], v[180:183], v[24:27]
	v_mfma_f32_16x16x32_bf16 v[12:15], v[72:75], v[188:191], v[12:15]
	v_mfma_f32_16x16x32_bf16 v[8:11], v[96:99], v[188:191], v[8:11]
	v_mfma_f32_16x16x32_bf16 v[52:55], v[108:111], v[152:155], v[52:55]
	v_mfma_f32_16x16x32_bf16 v[48:51], v[128:131], v[152:155], v[48:51]
	v_mfma_f32_16x16x32_bf16 v[36:39], v[108:111], v[160:163], v[36:39]
	v_mfma_f32_16x16x32_bf16 v[32:35], v[128:131], v[160:163], v[32:35]
	v_mfma_f32_16x16x32_bf16 v[20:23], v[108:111], v[168:171], v[20:23]
	v_mfma_f32_16x16x32_bf16 v[16:19], v[128:131], v[168:171], v[16:19]
	v_mfma_f32_16x16x32_bf16 v[4:7], v[108:111], v[184:187], v[4:7]
	v_mfma_f32_16x16x32_bf16 v[0:3], v[128:131], v[184:187], v[0:3]
	v_mfma_f32_16x16x32_bf16 v[52:55], v[116:119], v[156:159], v[52:55]
	v_mfma_f32_16x16x32_bf16 v[48:51], v[140:143], v[156:159], v[48:51]
	v_mfma_f32_16x16x32_bf16 v[36:39], v[116:119], v[164:167], v[36:39]
	v_mfma_f32_16x16x32_bf16 v[32:35], v[140:143], v[164:167], v[32:35]
	v_mfma_f32_16x16x32_bf16 v[20:23], v[116:119], v[180:183], v[20:23]
	v_mfma_f32_16x16x32_bf16 v[16:19], v[140:143], v[180:183], v[16:19]
	v_mfma_f32_16x16x32_bf16 v[4:7], v[116:119], v[188:191], v[4:7]
	v_mfma_f32_16x16x32_bf16 v[0:3], v[140:143], v[188:191], v[0:3]
	s_barrier
	s_add_i32 vcc_lo, vcc_lo, 2
	s_add_u32 s81, s81, 0x100
	s_addc_u32 s96, s96, 0
	s_mov_b64 s[78:79], s[82:83]

.LBB0_1293:
	s_cmp_eq_u32 s54, 5
	s_cbranch_scc0 .Lsk_epi
	v_readlane_b32 s78, v255, 5
	v_readlane_b32 s79, v255, 22
	v_mbcnt_lo_u32_b32 v192, -1, 0
	v_mbcnt_hi_u32_b32 v192, -1, v192
	v_lshlrev_b32_e32 v192, 4, v192
	s_lshr_b32 s78, s78, 6
	s_and_b32 s81, s1, 7
	s_lshl_b32 s81, s81, 5
	s_lshr_b32 s96, s1, 3
	s_add_i32 s81, s81, s96
	s_and_b32 s96, s96, 3
	s_lshr_b32 s81, s81, 2
	s_lshl_b32 s79, s79, 6
	s_add_i32 s79, s79, s81
	s_lshl_b32 s79, s79, 3
	s_add_i32 s79, s79, s78
	s_lshl_b32 s79, s79, 2
	s_add_u32 s98, s14, s79
	s_addc_u32 s99, s15, 0
	s_sub_u32 s98, s98, 0x39580000
	s_subb_u32 s99, s99, 0
	s_mul_i32 s81, s81, 24
	s_add_i32 s81, s81, s78
	s_lshl_b32 s81, s81, 15
	s_add_u32 s82, s14, s81
	s_addc_u32 s83, s15, 0
	s_sub_u32 s82, s82, 0x19800000
	s_subb_u32 s83, s83, 0
	s_cmp_eq_u32 s96, 3
	s_cbranch_scc1 .Lsk_fin
	s_lshl_b32 s96, s96, 18
	s_add_u32 s82, s82, s96
	s_addc_u32 s83, s83, 0
	global_store_dwordx4 v192, v[0:3], s[82:83] sc1
	global_store_dwordx4 v192, v[4:7], s[82:83] offset:1024 sc1
	global_store_dwordx4 v192, v[8:11], s[82:83] offset:2048 sc1
	global_store_dwordx4 v192, v[12:15], s[82:83] offset:3072 sc1
	s_add_u32 s78, s82, 0x1000
	s_addc_u32 s79, s83, 0
	global_store_dwordx4 v192, v[16:19], s[78:79] sc1
	global_store_dwordx4 v192, v[20:23], s[78:79] offset:1024 sc1
	global_store_dwordx4 v192, v[24:27], s[78:79] offset:2048 sc1
	global_store_dwordx4 v192, v[28:31], s[78:79] offset:3072 sc1
	s_add_u32 s78, s82, 0x2000
	s_addc_u32 s79, s83, 0
	global_store_dwordx4 v192, v[32:35], s[78:79] sc1
	global_store_dwordx4 v192, v[36:39], s[78:79] offset:1024 sc1
	global_store_dwordx4 v192, v[40:43], s[78:79] offset:2048 sc1
	global_store_dwordx4 v192, v[44:47], s[78:79] offset:3072 sc1
	s_add_u32 s78, s82, 0x3000
	s_addc_u32 s79, s83, 0
	global_store_dwordx4 v192, v[48:51], s[78:79] sc1
	global_store_dwordx4 v192, v[52:55], s[78:79] offset:1024 sc1
	global_store_dwordx4 v192, v[56:59], s[78:79] offset:2048 sc1
	global_store_dwordx4 v192, v[60:63], s[78:79] offset:3072 sc1
	s_add_u32 s78, s82, 0x4000
	s_addc_u32 s79, s83, 0
	global_store_dwordx4 v192, v[68:71], s[78:79] sc1
	global_store_dwordx4 v192, v[76:79], s[78:79] offset:1024 sc1
	global_store_dwordx4 v192, v[80:83], s[78:79] offset:2048 sc1
	global_store_dwordx4 v192, v[84:87], s[78:79] offset:3072 sc1
	s_add_u32 s78, s82, 0x5000
	s_addc_u32 s79, s83, 0
	global_store_dwordx4 v192, v[92:95], s[78:79] sc1
	global_store_dwordx4 v192, v[100:103], s[78:79] offset:1024 sc1
	global_store_dwordx4 v192, v[104:107], s[78:79] offset:2048 sc1
	global_store_dwordx4 v192, v[112:115], s[78:79] offset:3072 sc1
	s_add_u32 s78, s82, 0x6000
	s_addc_u32 s79, s83, 0
	global_store_dwordx4 v192, v[120:123], s[78:79] sc1
	global_store_dwordx4 v192, v[124:127], s[78:79] offset:1024 sc1
	global_store_dwordx4 v192, v[132:135], s[78:79] offset:2048 sc1
	global_store_dwordx4 v192, v[136:139], s[78:79] offset:3072 sc1
	s_add_u32 s78, s82, 0x7000
	s_addc_u32 s79, s83, 0
	global_store_dwordx4 v192, v[144:147], s[78:79] sc1
	global_store_dwordx4 v192, v[148:151], s[78:79] offset:1024 sc1
	global_store_dwordx4 v192, v[172:175], s[78:79] offset:2048 sc1
	global_store_dwordx4 v192, v[176:179], s[78:79] offset:3072 sc1
	s_waitcnt vmcnt(0)
	v_mov_b32_e32 v193, 1
	s_mov_b64 exec, 1
	global_atomic_add v217, v193, s[98:99]
	s_mov_b64 exec, -1
	s_branch .Lsk_after_epi
.Lsk_fin:
	s_mov_b32 s96, 0
.Lsk_spin:
	global_load_dword v193, v217, s[98:99] sc1
	s_waitcnt vmcnt(0)
	v_readfirstlane_b32 s32, v193
	s_cmp_ge_u32 s32, 3
	s_cbranch_scc1 .Lsk_ready
	s_sleep 2
	s_add_i32 s96, s96, 1
	s_cmp_lt_u32 s96, 0x40000
	s_cbranch_scc1 .Lsk_spin
.Lsk_ready:
	global_load_dwordx4 v[64:67], v192, s[82:83] sc1
	global_load_dwordx4 v[72:75], v192, s[82:83] offset:1024 sc1
	global_load_dwordx4 v[88:91], v192, s[82:83] offset:2048 sc1
	global_load_dwordx4 v[96:99], v192, s[82:83] offset:3072 sc1
	s_add_u32 s78, s82, 0x1000
	s_addc_u32 s79, s83, 0
	global_load_dwordx4 v[108:111], v192, s[78:79] sc1
	global_load_dwordx4 v[116:119], v192, s[78:79] offset:1024 sc1
	global_load_dwordx4 v[128:131], v192, s[78:79] offset:2048 sc1
	global_load_dwordx4 v[140:143], v192, s[78:79] offset:3072 sc1
	s_add_u32 s78, s82, 0x2000
	s_addc_u32 s79, s83, 0
	global_load_dwordx4 v[152:155], v192, s[78:79] sc1
	global_load_dwordx4 v[156:159], v192, s[78:79] offset:1024 sc1
	global_load_dwordx4 v[160:163], v192, s[78:79] offset:2048 sc1
	global_load_dwordx4 v[164:167], v192, s[78:79] offset:3072 sc1
	s_add_u32 s78, s82, 0x3000
	s_addc_u32 s79, s83, 0
	global_load_dwordx4 v[168:171], v192, s[78:79] sc1
	global_load_dwordx4 v[180:183], v192, s[78:79] offset:1024 sc1
	global_load_dwordx4 v[184:187], v192, s[78:79] offset:2048 sc1
	global_load_dwordx4 v[188:191], v192, s[78:79] offset:3072 sc1
	s_waitcnt vmcnt(8)
	v_pk_add_f32 v[0:1], v[0:1], v[64:65]
	v_pk_add_f32 v[2:3], v[2:3], v[66:67]
	v_pk_add_f32 v[4:5], v[4:5], v[72:73]
	v_pk_add_f32 v[6:7], v[6:7], v[74:75]
	v_pk_add_f32 v[8:9], v[8:9], v[88:89]
	v_pk_add_f32 v[10:11], v[10:11], v[90:91]
	v_pk_add_f32 v[12:13], v[12:13], v[96:97]
	v_pk_add_f32 v[14:15], v[14:15], v[98:99]
	v_pk_add_f32 v[16:17], v[16:17], v[108:109]
	v_pk_add_f32 v[18:19], v[18:19], v[110:111]
	v_pk_add_f32 v[20:21], v[20:21], v[116:117]
	v_pk_add_f32 v[22:23], v[22:23], v[118:119]
	v_pk_add_f32 v[24:25], v[24:25], v[128:129]
	v_pk_add_f32 v[26:27], v[26:27], v[130:131]
	v_pk_add_f32 v[28:29], v[28:29], v[140:141]
	v_pk_add_f32 v[30:31], v[30:31], v[142:143]
	s_add_u32 s78, s82, 0x4000
	s_addc_u32 s79, s83, 0
	global_load_dwordx4 v[64:67], v192, s[78:79] sc1
	global_load_dwordx4 v[72:75], v192, s[78:79] offset:1024 sc1
	global_load_dwordx4 v[88:91], v192, s[78:79] offset:2048 sc1
	global_load_dwordx4 v[96:99], v192, s[78:79] offset:3072 sc1
	s_add_u32 s78, s82, 0x5000
	s_addc_u32 s79, s83, 0
	global_load_dwordx4 v[108:111], v192, s[78:79] sc1
	global_load_dwordx4 v[116:119], v192, s[78:79] offset:1024 sc1
	global_load_dwordx4 v[128:131], v192, s[78:79] offset:2048 sc1
	global_load_dwordx4 v[140:143], v192, s[78:79] offset:3072 sc1
	s_waitcnt vmcnt(8)
	v_pk_add_f32 v[32:33], v[32:33], v[152:153]
	v_pk_add_f32 v[34:35], v[34:35], v[154:155]
	v_pk_add_f32 v[36:37], v[36:37], v[156:157]
	v_pk_add_f32 v[38:39], v[38:39], v[158:159]
	v_pk_add_f32 v[40:41], v[40:41], v[160:161]
	v_pk_add_f32 v[42:43], v[42:43], v[162:163]
	v_pk_add_f32 v[44:45], v[44:45], v[164:165]
	v_pk_add_f32 v[46:47], v[46:47], v[166:167]
	v_pk_add_f32 v[48:49], v[48:49], v[168:169]
	v_pk_add_f32 v[50:51], v[50:51], v[170:171]
	v_pk_add_f32 v[52:53], v[52:53], v[180:181]
	v_pk_add_f32 v[54:55], v[54:55], v[182:183]
	v_pk_add_f32 v[56:57], v[56:57], v[184:185]
	v_pk_add_f32 v[58:59], v[58:59], v[186:187]
	v_pk_add_f32 v[60:61], v[60:61], v[188:189]
	v_pk_add_f32 v[62:63], v[62:63], v[190:191]
	s_add_u32 s78, s82, 0x6000
	s_addc_u32 s79, s83, 0
	global_load_dwordx4 v[152:155], v192, s[78:79] sc1
	global_load_dwordx4 v[156:159], v192, s[78:79] offset:1024 sc1
	global_load_dwordx4 v[160:163], v192, s[78:79] offset:2048 sc1
	global_load_dwordx4 v[164:167], v192, s[78:79] offset:3072 sc1
	s_add_u32 s78, s82, 0x7000
	s_addc_u32 s79, s83, 0
	global_load_dwordx4 v[168:171], v192, s[78:79] sc1
	global_load_dwordx4 v[180:183], v192, s[78:79] offset:1024 sc1
	global_load_dwordx4 v[184:187], v192, s[78:79] offset:2048 sc1
	global_load_dwordx4 v[188:191], v192, s[78:79] offset:3072 sc1
	s_waitcnt vmcnt(8)
	v_pk_add_f32 v[68:69], v[68:69], v[64:65]
	v_pk_add_f32 v[70:71], v[70:71], v[66:67]
	v_pk_add_f32 v[76:77], v[76:77], v[72:73]
	v_pk_add_f32 v[78:79], v[78:79], v[74:75]
	v_pk_add_f32 v[80:81], v[80:81], v[88:89]
	v_pk_add_f32 v[82:83], v[82:83], v[90:91]
	v_pk_add_f32 v[84:85], v[84:85], v[96:97]
	v_pk_add_f32 v[86:87], v[86:87], v[98:99]
	v_pk_add_f32 v[92:93], v[92:93], v[108:109]
	v_pk_add_f32 v[94:95], v[94:95], v[110:111]
	v_pk_add_f32 v[100:101], v[100:101], v[116:117]
	v_pk_add_f32 v[102:103], v[102:103], v[118:119]
	v_pk_add_f32 v[104:105], v[104:105], v[128:129]
	v_pk_add_f32 v[106:107], v[106:107], v[130:131]
	v_pk_add_f32 v[112:113], v[112:113], v[140:141]
	v_pk_add_f32 v[114:115], v[114:115], v[142:143]
	s_add_u32 s78, s82, 0x40000
	s_addc_u32 s79, s83, 0
	global_load_dwordx4 v[64:67], v192, s[78:79] sc1
	global_load_dwordx4 v[72:75], v192, s[78:79] offset:1024 sc1
	global_load_dwordx4 v[88:91], v192, s[78:79] offset:2048 sc1
	global_load_dwordx4 v[96:99], v192, s[78:79] offset:3072 sc1
	s_add_u32 s78, s82, 0x41000
	s_addc_u32 s79, s83, 0
	global_load_dwordx4 v[108:111], v192, s[78:79] sc1
	global_load_dwordx4 v[116:119], v192, s[78:79] offset:1024 sc1
	global_load_dwordx4 v[128:131], v192, s[78:79] offset:2048 sc1
	global_load_dwordx4 v[140:143], v192, s[78:79] offset:3072 sc1
	s_waitcnt vmcnt(8)
	v_pk_add_f32 v[120:121], v[120:121], v[152:153]
	v_pk_add_f32 v[122:123], v[122:123], v[154:155]
	v_pk_add_f32 v[124:125], v[124:125], v[156:157]
	v_pk_add_f32 v[126:127], v[126:127], v[158:159]
	v_pk_add_f32 v[132:133], v[132:133], v[160:161]
	v_pk_add_f32 v[134:135], v[134:135], v[162:163]
	v_pk_add_f32 v[136:137], v[136:137], v[164:165]
	v_pk_add_f32 v[138:139], v[138:139], v[166:167]
	v_pk_add_f32 v[144:145], v[144:145], v[168:169]
	v_pk_add_f32 v[146:147], v[146:147], v[170:171]
	v_pk_add_f32 v[148:149], v[148:149], v[180:181]
	v_pk_add_f32 v[150:151], v[150:151], v[182:183]
	v_pk_add_f32 v[172:173], v[172:173], v[184:185]
	v_pk_add_f32 v[174:175], v[174:175], v[186:187]
	v_pk_add_f32 v[176:177], v[176:177], v[188:189]
	v_pk_add_f32 v[178:179], v[178:179], v[190:191]
	s_add_u32 s78, s82, 0x42000
	s_addc_u32 s79, s83, 0
	global_load_dwordx4 v[152:155], v192, s[78:79] sc1
	global_load_dwordx4 v[156:159], v192, s[78:79] offset:1024 sc1
	global_load_dwordx4 v[160:163], v192, s[78:79] offset:2048 sc1
	global_load_dwordx4 v[164:167], v192, s[78:79] offset:3072 sc1
	s_add_u32 s78, s82, 0x43000
	s_addc_u32 s79, s83, 0
	global_load_dwordx4 v[168:171], v192, s[78:79] sc1
	global_load_dwordx4 v[180:183], v192, s[78:79] offset:1024 sc1
	global_load_dwordx4 v[184:187], v192, s[78:79] offset:2048 sc1
	global_load_dwordx4 v[188:191], v192, s[78:79] offset:3072 sc1
	s_waitcnt vmcnt(8)
	v_pk_add_f32 v[0:1], v[0:1], v[64:65]
	v_pk_add_f32 v[2:3], v[2:3], v[66:67]
	v_pk_add_f32 v[4:5], v[4:5], v[72:73]
	v_pk_add_f32 v[6:7], v[6:7], v[74:75]
	v_pk_add_f32 v[8:9], v[8:9], v[88:89]
	v_pk_add_f32 v[10:11], v[10:11], v[90:91]
	v_pk_add_f32 v[12:13], v[12:13], v[96:97]
	v_pk_add_f32 v[14:15], v[14:15], v[98:99]
	v_pk_add_f32 v[16:17], v[16:17], v[108:109]
	v_pk_add_f32 v[18:19], v[18:19], v[110:111]
	v_pk_add_f32 v[20:21], v[20:21], v[116:117]
	v_pk_add_f32 v[22:23], v[22:23], v[118:119]
	v_pk_add_f32 v[24:25], v[24:25], v[128:129]
	v_pk_add_f32 v[26:27], v[26:27], v[130:131]
	v_pk_add_f32 v[28:29], v[28:29], v[140:141]
	v_pk_add_f32 v[30:31], v[30:31], v[142:143]
	s_add_u32 s78, s82, 0x44000
	s_addc_u32 s79, s83, 0
	global_load_dwordx4 v[64:67], v192, s[78:79] sc1
	global_load_dwordx4 v[72:75], v192, s[78:79] offset:1024 sc1
	global_load_dwordx4 v[88:91], v192, s[78:79] offset:2048 sc1
	global_load_dwordx4 v[96:99], v192, s[78:79] offset:3072 sc1
	s_add_u32 s78, s82, 0x45000
	s_addc_u32 s79, s83, 0
	global_load_dwordx4 v[108:111], v192, s[78:79] sc1
	global_load_dwordx4 v[116:119], v192, s[78:79] offset:1024 sc1
	global_load_dwordx4 v[128:131], v192, s[78:79] offset:2048 sc1
	global_load_dwordx4 v[140:143], v192, s[78:79] offset:3072 sc1
	s_waitcnt vmcnt(8)
	v_pk_add_f32 v[32:33], v[32:33], v[152:153]
	v_pk_add_f32 v[34:35], v[34:35], v[154:155]
	v_pk_add_f32 v[36:37], v[36:37], v[156:157]
	v_pk_add_f32 v[38:39], v[38:39], v[158:159]
	v_pk_add_f32 v[40:41], v[40:41], v[160:161]
	v_pk_add_f32 v[42:43], v[42:43], v[162:163]
	v_pk_add_f32 v[44:45], v[44:45], v[164:165]
	v_pk_add_f32 v[46:47], v[46:47], v[166:167]
	v_pk_add_f32 v[48:49], v[48:49], v[168:169]
	v_pk_add_f32 v[50:51], v[50:51], v[170:171]
	v_pk_add_f32 v[52:53], v[52:53], v[180:181]
	v_pk_add_f32 v[54:55], v[54:55], v[182:183]
	v_pk_add_f32 v[56:57], v[56:57], v[184:185]
	v_pk_add_f32 v[58:59], v[58:59], v[186:187]
	v_pk_add_f32 v[60:61], v[60:61], v[188:189]
	v_pk_add_f32 v[62:63], v[62:63], v[190:191]
	s_add_u32 s78, s82, 0x46000
	s_addc_u32 s79, s83, 0
	global_load_dwordx4 v[152:155], v192, s[78:79] sc1
	global_load_dwordx4 v[156:159], v192, s[78:79] offset:1024 sc1
	global_load_dwordx4 v[160:163], v192, s[78:79] offset:2048 sc1
	global_load_dwordx4 v[164:167], v192, s[78:79] offset:3072 sc1
	s_add_u32 s78, s82, 0x47000
	s_addc_u32 s79, s83, 0
	global_load_dwordx4 v[168:171], v192, s[78:79] sc1
	global_load_dwordx4 v[180:183], v192, s[78:79] offset:1024 sc1
	global_load_dwordx4 v[184:187], v192, s[78:79] offset:2048 sc1
	global_load_dwordx4 v[188:191], v192, s[78:79] offset:3072 sc1
	s_waitcnt vmcnt(8)
	v_pk_add_f32 v[68:69], v[68:69], v[64:65]
	v_pk_add_f32 v[70:71], v[70:71], v[66:67]
	v_pk_add_f32 v[76:77], v[76:77], v[72:73]
	v_pk_add_f32 v[78:79], v[78:79], v[74:75]
	v_pk_add_f32 v[80:81], v[80:81], v[88:89]
	v_pk_add_f32 v[82:83], v[82:83], v[90:91]
	v_pk_add_f32 v[84:85], v[84:85], v[96:97]
	v_pk_add_f32 v[86:87], v[86:87], v[98:99]
	v_pk_add_f32 v[92:93], v[92:93], v[108:109]
	v_pk_add_f32 v[94:95], v[94:95], v[110:111]
	v_pk_add_f32 v[100:101], v[100:101], v[116:117]
	v_pk_add_f32 v[102:103], v[102:103], v[118:119]
	v_pk_add_f32 v[104:105], v[104:105], v[128:129]
	v_pk_add_f32 v[106:107], v[106:107], v[130:131]
	v_pk_add_f32 v[112:113], v[112:113], v[140:141]
	v_pk_add_f32 v[114:115], v[114:115], v[142:143]
	s_add_u32 s78, s82, 0x80000
	s_addc_u32 s79, s83, 0
	global_load_dwordx4 v[64:67], v192, s[78:79] sc1
	global_load_dwordx4 v[72:75], v192, s[78:79] offset:1024 sc1
	global_load_dwordx4 v[88:91], v192, s[78:79] offset:2048 sc1
	global_load_dwordx4 v[96:99], v192, s[78:79] offset:3072 sc1
	s_add_u32 s78, s82, 0x81000
	s_addc_u32 s79, s83, 0
	global_load_dwordx4 v[108:111], v192, s[78:79] sc1
	global_load_dwordx4 v[116:119], v192, s[78:79] offset:1024 sc1
	global_load_dwordx4 v[128:131], v192, s[78:79] offset:2048 sc1
	global_load_dwordx4 v[140:143], v192, s[78:79] offset:3072 sc1
	s_waitcnt vmcnt(8)
	v_pk_add_f32 v[120:121], v[120:121], v[152:153]
	v_pk_add_f32 v[122:123], v[122:123], v[154:155]
	v_pk_add_f32 v[124:125], v[124:125], v[156:157]
	v_pk_add_f32 v[126:127], v[126:127], v[158:159]
	v_pk_add_f32 v[132:133], v[132:133], v[160:161]
	v_pk_add_f32 v[134:135], v[134:135], v[162:163]
	v_pk_add_f32 v[136:137], v[136:137], v[164:165]
	v_pk_add_f32 v[138:139], v[138:139], v[166:167]
	v_pk_add_f32 v[144:145], v[144:145], v[168:169]
	v_pk_add_f32 v[146:147], v[146:147], v[170:171]
	v_pk_add_f32 v[148:149], v[148:149], v[180:181]
	v_pk_add_f32 v[150:151], v[150:151], v[182:183]
	v_pk_add_f32 v[172:173], v[172:173], v[184:185]
	v_pk_add_f32 v[174:175], v[174:175], v[186:187]
	v_pk_add_f32 v[176:177], v[176:177], v[188:189]
	v_pk_add_f32 v[178:179], v[178:179], v[190:191]
	s_add_u32 s78, s82, 0x82000
	s_addc_u32 s79, s83, 0
	global_load_dwordx4 v[152:155], v192, s[78:79] sc1
	global_load_dwordx4 v[156:159], v192, s[78:79] offset:1024 sc1
	global_load_dwordx4 v[160:163], v192, s[78:79] offset:2048 sc1
	global_load_dwordx4 v[164:167], v192, s[78:79] offset:3072 sc1
	s_add_u32 s78, s82, 0x83000
	s_addc_u32 s79, s83, 0
	global_load_dwordx4 v[168:171], v192, s[78:79] sc1
	global_load_dwordx4 v[180:183], v192, s[78:79] offset:1024 sc1
	global_load_dwordx4 v[184:187], v192, s[78:79] offset:2048 sc1
	global_load_dwordx4 v[188:191], v192, s[78:79] offset:3072 sc1
	s_waitcnt vmcnt(8)
	v_pk_add_f32 v[0:1], v[0:1], v[64:65]
	v_pk_add_f32 v[2:3], v[2:3], v[66:67]
	v_pk_add_f32 v[4:5], v[4:5], v[72:73]
	v_pk_add_f32 v[6:7], v[6:7], v[74:75]
	v_pk_add_f32 v[8:9], v[8:9], v[88:89]
	v_pk_add_f32 v[10:11], v[10:11], v[90:91]
	v_pk_add_f32 v[12:13], v[12:13], v[96:97]
	v_pk_add_f32 v[14:15], v[14:15], v[98:99]
	v_pk_add_f32 v[16:17], v[16:17], v[108:109]
	v_pk_add_f32 v[18:19], v[18:19], v[110:111]
	v_pk_add_f32 v[20:21], v[20:21], v[116:117]
	v_pk_add_f32 v[22:23], v[22:23], v[118:119]
	v_pk_add_f32 v[24:25], v[24:25], v[128:129]
	v_pk_add_f32 v[26:27], v[26:27], v[130:131]
	v_pk_add_f32 v[28:29], v[28:29], v[140:141]
	v_pk_add_f32 v[30:31], v[30:31], v[142:143]
	s_add_u32 s78, s82, 0x84000
	s_addc_u32 s79, s83, 0
	global_load_dwordx4 v[64:67], v192, s[78:79] sc1
	global_load_dwordx4 v[72:75], v192, s[78:79] offset:1024 sc1
	global_load_dwordx4 v[88:91], v192, s[78:79] offset:2048 sc1
	global_load_dwordx4 v[96:99], v192, s[78:79] offset:3072 sc1
	s_add_u32 s78, s82, 0x85000
	s_addc_u32 s79, s83, 0
	global_load_dwordx4 v[108:111], v192, s[78:79] sc1
	global_load_dwordx4 v[116:119], v192, s[78:79] offset:1024 sc1
	global_load_dwordx4 v[128:131], v192, s[78:79] offset:2048 sc1
	global_load_dwordx4 v[140:143], v192, s[78:79] offset:3072 sc1
	s_waitcnt vmcnt(8)
	v_pk_add_f32 v[32:33], v[32:33], v[152:153]
	v_pk_add_f32 v[34:35], v[34:35], v[154:155]
	v_pk_add_f32 v[36:37], v[36:37], v[156:157]
	v_pk_add_f32 v[38:39], v[38:39], v[158:159]
	v_pk_add_f32 v[40:41], v[40:41], v[160:161]
	v_pk_add_f32 v[42:43], v[42:43], v[162:163]
	v_pk_add_f32 v[44:45], v[44:45], v[164:165]
	v_pk_add_f32 v[46:47], v[46:47], v[166:167]
	v_pk_add_f32 v[48:49], v[48:49], v[168:169]
	v_pk_add_f32 v[50:51], v[50:51], v[170:171]
	v_pk_add_f32 v[52:53], v[52:53], v[180:181]
	v_pk_add_f32 v[54:55], v[54:55], v[182:183]
	v_pk_add_f32 v[56:57], v[56:57], v[184:185]
	v_pk_add_f32 v[58:59], v[58:59], v[186:187]
	v_pk_add_f32 v[60:61], v[60:61], v[188:189]
	v_pk_add_f32 v[62:63], v[62:63], v[190:191]
	s_add_u32 s78, s82, 0x86000
	s_addc_u32 s79, s83, 0
	global_load_dwordx4 v[152:155], v192, s[78:79] sc1
	global_load_dwordx4 v[156:159], v192, s[78:79] offset:1024 sc1
	global_load_dwordx4 v[160:163], v192, s[78:79] offset:2048 sc1
	global_load_dwordx4 v[164:167], v192, s[78:79] offset:3072 sc1
	s_add_u32 s78, s82, 0x87000
	s_addc_u32 s79, s83, 0
	global_load_dwordx4 v[168:171], v192, s[78:79] sc1
	global_load_dwordx4 v[180:183], v192, s[78:79] offset:1024 sc1
	global_load_dwordx4 v[184:187], v192, s[78:79] offset:2048 sc1
	global_load_dwordx4 v[188:191], v192, s[78:79] offset:3072 sc1
	s_waitcnt vmcnt(8)
	v_pk_add_f32 v[68:69], v[68:69], v[64:65]
	v_pk_add_f32 v[70:71], v[70:71], v[66:67]
	v_pk_add_f32 v[76:77], v[76:77], v[72:73]
	v_pk_add_f32 v[78:79], v[78:79], v[74:75]
	v_pk_add_f32 v[80:81], v[80:81], v[88:89]
	v_pk_add_f32 v[82:83], v[82:83], v[90:91]
	v_pk_add_f32 v[84:85], v[84:85], v[96:97]
	v_pk_add_f32 v[86:87], v[86:87], v[98:99]
	v_pk_add_f32 v[92:93], v[92:93], v[108:109]
	v_pk_add_f32 v[94:95], v[94:95], v[110:111]
	v_pk_add_f32 v[100:101], v[100:101], v[116:117]
	v_pk_add_f32 v[102:103], v[102:103], v[118:119]
	v_pk_add_f32 v[104:105], v[104:105], v[128:129]
	v_pk_add_f32 v[106:107], v[106:107], v[130:131]
	v_pk_add_f32 v[112:113], v[112:113], v[140:141]
	v_pk_add_f32 v[114:115], v[114:115], v[142:143]
	s_waitcnt vmcnt(0)
	v_pk_add_f32 v[120:121], v[120:121], v[152:153]
	v_pk_add_f32 v[122:123], v[122:123], v[154:155]
	v_pk_add_f32 v[124:125], v[124:125], v[156:157]
	v_pk_add_f32 v[126:127], v[126:127], v[158:159]
	v_pk_add_f32 v[132:133], v[132:133], v[160:161]
	v_pk_add_f32 v[134:135], v[134:135], v[162:163]
	v_pk_add_f32 v[136:137], v[136:137], v[164:165]
	v_pk_add_f32 v[138:139], v[138:139], v[166:167]
	v_pk_add_f32 v[144:145], v[144:145], v[168:169]
	v_pk_add_f32 v[146:147], v[146:147], v[170:171]
	v_pk_add_f32 v[148:149], v[148:149], v[180:181]
	v_pk_add_f32 v[150:151], v[150:151], v[182:183]
	v_pk_add_f32 v[172:173], v[172:173], v[184:185]
	v_pk_add_f32 v[174:175], v[174:175], v[186:187]
	v_pk_add_f32 v[176:177], v[176:177], v[188:189]
	v_pk_add_f32 v[178:179], v[178:179], v[190:191]

.Lsk_after_epi:
	s_and_b64 vcc, exec, s[4:5]
	s_mov_b64 s[4:5], -1
	s_cbranch_vccnz .LBB0_1270
	s_andn2_b64 vcc, exec, s[18:19]
	s_cbranch_vccnz .LBB0_1269
	s_barrier
	s_branch .LBB0_1269
